# same as previous best plus a wait-state pad after v_readfirstlane in the rewritten lr projection
# baseline (speedup 1.0000x reference)
.LBB0_552:
	s_cmpk_lg_i32 s68, 0x100
	s_cbranch_scc1 .Llr_orig
	v_mov_b32_e32 v0, v188
	s_nop 0
	v_readfirstlane_b32 s2, v0
	v_and_b32_e32 v1, 63, v0
	s_nop 3
	s_lshr_b32 s2, s2, 6
	s_and_b32 s3, s2, 3
	s_lshr_b32 s4, s2, 2
	s_lshl_b32 s5, s30, 2
	s_add_i32 s5, s5, s3
	v_and_b32_e32 v2, 15, v1
	v_lshrrev_b32_e32 v3, 4, v1
	v_lshlrev_b32_e32 v136, 12, v2
	v_lshl_add_u32 v136, v3, 4, v136
	s_lshl_b32 s98, s4, 11
	v_add_u32_e32 v137, s98, v136
	s_lshl_b32 s99, s5, 16
	v_add_u32_e32 v136, s99, v137
	s_add_u32 s100, s50, 0x200000
	s_addc_u32 s101, s51, 0
	v_mov_b32_e32 v4, 0
	v_mov_b32_e32 v5, 0
	v_mov_b32_e32 v6, 0
	v_mov_b32_e32 v7, 0
	global_load_dwordx4 v[8:11], v136, s[58:59]
	global_load_dwordx4 v[12:15], v137, s[100:101]
	global_load_dwordx4 v[16:19], v136, s[58:59] offset:64
	global_load_dwordx4 v[20:23], v137, s[100:101] offset:64
	global_load_dwordx4 v[24:27], v136, s[58:59] offset:128
	global_load_dwordx4 v[28:31], v137, s[100:101] offset:128
	global_load_dwordx4 v[32:35], v136, s[58:59] offset:192
	global_load_dwordx4 v[36:39], v137, s[100:101] offset:192
	global_load_dwordx4 v[40:43], v136, s[58:59] offset:256
	global_load_dwordx4 v[44:47], v137, s[100:101] offset:256
	global_load_dwordx4 v[48:51], v136, s[58:59] offset:320
	global_load_dwordx4 v[52:55], v137, s[100:101] offset:320
	global_load_dwordx4 v[56:59], v136, s[58:59] offset:384
	global_load_dwordx4 v[60:63], v137, s[100:101] offset:384
	global_load_dwordx4 v[64:67], v136, s[58:59] offset:448
	global_load_dwordx4 v[68:71], v137, s[100:101] offset:448
	global_load_dwordx4 v[72:75], v136, s[58:59] offset:512
	global_load_dwordx4 v[76:79], v137, s[100:101] offset:512
	global_load_dwordx4 v[80:83], v136, s[58:59] offset:576
	global_load_dwordx4 v[84:87], v137, s[100:101] offset:576
	global_load_dwordx4 v[88:91], v136, s[58:59] offset:640
	global_load_dwordx4 v[92:95], v137, s[100:101] offset:640
	global_load_dwordx4 v[96:99], v136, s[58:59] offset:704
	global_load_dwordx4 v[100:103], v137, s[100:101] offset:704
	global_load_dwordx4 v[104:107], v136, s[58:59] offset:768
	global_load_dwordx4 v[108:111], v137, s[100:101] offset:768
	global_load_dwordx4 v[112:115], v136, s[58:59] offset:832
	global_load_dwordx4 v[116:119], v137, s[100:101] offset:832
	global_load_dwordx4 v[120:123], v136, s[58:59] offset:896
	global_load_dwordx4 v[124:127], v137, s[100:101] offset:896
	global_load_dwordx4 v[128:131], v136, s[58:59] offset:960
	global_load_dwordx4 v[132:135], v137, s[100:101] offset:960
	s_waitcnt vmcnt(30)
	v_mfma_f32_16x16x32_bf16 v[4:7], v[8:11], v[12:15], v[4:7]
	global_load_dwordx4 v[8:11], v136, s[58:59] offset:1024
	global_load_dwordx4 v[12:15], v137, s[100:101] offset:1024
	s_waitcnt vmcnt(30)
	v_mfma_f32_16x16x32_bf16 v[4:7], v[16:19], v[20:23], v[4:7]
	global_load_dwordx4 v[16:19], v136, s[58:59] offset:1088
	global_load_dwordx4 v[20:23], v137, s[100:101] offset:1088
	s_waitcnt vmcnt(30)
	v_mfma_f32_16x16x32_bf16 v[4:7], v[24:27], v[28:31], v[4:7]
	global_load_dwordx4 v[24:27], v136, s[58:59] offset:1152
	global_load_dwordx4 v[28:31], v137, s[100:101] offset:1152
	s_waitcnt vmcnt(30)
	v_mfma_f32_16x16x32_bf16 v[4:7], v[32:35], v[36:39], v[4:7]
	global_load_dwordx4 v[32:35], v136, s[58:59] offset:1216
	global_load_dwordx4 v[36:39], v137, s[100:101] offset:1216
	s_waitcnt vmcnt(30)
	v_mfma_f32_16x16x32_bf16 v[4:7], v[40:43], v[44:47], v[4:7]
	global_load_dwordx4 v[40:43], v136, s[58:59] offset:1280
	global_load_dwordx4 v[44:47], v137, s[100:101] offset:1280
	s_waitcnt vmcnt(30)
	v_mfma_f32_16x16x32_bf16 v[4:7], v[48:51], v[52:55], v[4:7]
	global_load_dwordx4 v[48:51], v136, s[58:59] offset:1344
	global_load_dwordx4 v[52:55], v137, s[100:101] offset:1344
	s_waitcnt vmcnt(30)
	v_mfma_f32_16x16x32_bf16 v[4:7], v[56:59], v[60:63], v[4:7]
	global_load_dwordx4 v[56:59], v136, s[58:59] offset:1408
	global_load_dwordx4 v[60:63], v137, s[100:101] offset:1408
	s_waitcnt vmcnt(30)
	v_mfma_f32_16x16x32_bf16 v[4:7], v[64:67], v[68:71], v[4:7]
	global_load_dwordx4 v[64:67], v136, s[58:59] offset:1472
	global_load_dwordx4 v[68:71], v137, s[100:101] offset:1472
	s_waitcnt vmcnt(30)
	v_mfma_f32_16x16x32_bf16 v[4:7], v[72:75], v[76:79], v[4:7]
	global_load_dwordx4 v[72:75], v136, s[58:59] offset:1536
	global_load_dwordx4 v[76:79], v137, s[100:101] offset:1536
	s_waitcnt vmcnt(30)
	v_mfma_f32_16x16x32_bf16 v[4:7], v[80:83], v[84:87], v[4:7]
	global_load_dwordx4 v[80:83], v136, s[58:59] offset:1600
	global_load_dwordx4 v[84:87], v137, s[100:101] offset:1600
	s_waitcnt vmcnt(30)
	v_mfma_f32_16x16x32_bf16 v[4:7], v[88:91], v[92:95], v[4:7]
	global_load_dwordx4 v[88:91], v136, s[58:59] offset:1664
	global_load_dwordx4 v[92:95], v137, s[100:101] offset:1664
	s_waitcnt vmcnt(30)
	v_mfma_f32_16x16x32_bf16 v[4:7], v[96:99], v[100:103], v[4:7]
	global_load_dwordx4 v[96:99], v136, s[58:59] offset:1728
	global_load_dwordx4 v[100:103], v137, s[100:101] offset:1728
	s_waitcnt vmcnt(30)
	v_mfma_f32_16x16x32_bf16 v[4:7], v[104:107], v[108:111], v[4:7]
	global_load_dwordx4 v[104:107], v136, s[58:59] offset:1792
	global_load_dwordx4 v[108:111], v137, s[100:101] offset:1792
	s_waitcnt vmcnt(30)
	v_mfma_f32_16x16x32_bf16 v[4:7], v[112:115], v[116:119], v[4:7]
	global_load_dwordx4 v[112:115], v136, s[58:59] offset:1856
	global_load_dwordx4 v[116:119], v137, s[100:101] offset:1856
	s_waitcnt vmcnt(30)
	v_mfma_f32_16x16x32_bf16 v[4:7], v[120:123], v[124:127], v[4:7]
	global_load_dwordx4 v[120:123], v136, s[58:59] offset:1920
	global_load_dwordx4 v[124:127], v137, s[100:101] offset:1920
	s_waitcnt vmcnt(30)
	v_mfma_f32_16x16x32_bf16 v[4:7], v[128:131], v[132:135], v[4:7]
	global_load_dwordx4 v[128:131], v136, s[58:59] offset:1984
	global_load_dwordx4 v[132:135], v137, s[100:101] offset:1984
	s_waitcnt vmcnt(30)
	v_mfma_f32_16x16x32_bf16 v[4:7], v[8:11], v[12:15], v[4:7]
	s_waitcnt vmcnt(28)
	v_mfma_f32_16x16x32_bf16 v[4:7], v[16:19], v[20:23], v[4:7]
	s_waitcnt vmcnt(26)
	v_mfma_f32_16x16x32_bf16 v[4:7], v[24:27], v[28:31], v[4:7]
	s_waitcnt vmcnt(24)
	v_mfma_f32_16x16x32_bf16 v[4:7], v[32:35], v[36:39], v[4:7]
	s_waitcnt vmcnt(22)
	v_mfma_f32_16x16x32_bf16 v[4:7], v[40:43], v[44:47], v[4:7]
	s_waitcnt vmcnt(20)
	v_mfma_f32_16x16x32_bf16 v[4:7], v[48:51], v[52:55], v[4:7]
	s_waitcnt vmcnt(18)
	v_mfma_f32_16x16x32_bf16 v[4:7], v[56:59], v[60:63], v[4:7]
	s_waitcnt vmcnt(16)
	v_mfma_f32_16x16x32_bf16 v[4:7], v[64:67], v[68:71], v[4:7]
	s_waitcnt vmcnt(14)
	v_mfma_f32_16x16x32_bf16 v[4:7], v[72:75], v[76:79], v[4:7]
	s_waitcnt vmcnt(12)
	v_mfma_f32_16x16x32_bf16 v[4:7], v[80:83], v[84:87], v[4:7]
	s_waitcnt vmcnt(10)
	v_mfma_f32_16x16x32_bf16 v[4:7], v[88:91], v[92:95], v[4:7]
	s_waitcnt vmcnt(8)
	v_mfma_f32_16x16x32_bf16 v[4:7], v[96:99], v[100:103], v[4:7]
	s_waitcnt vmcnt(6)
	v_mfma_f32_16x16x32_bf16 v[4:7], v[104:107], v[108:111], v[4:7]
	s_waitcnt vmcnt(4)
	v_mfma_f32_16x16x32_bf16 v[4:7], v[112:115], v[116:119], v[4:7]
	s_waitcnt vmcnt(2)
	v_mfma_f32_16x16x32_bf16 v[4:7], v[120:123], v[124:127], v[4:7]
	s_waitcnt vmcnt(0)
	v_mfma_f32_16x16x32_bf16 v[4:7], v[128:131], v[132:135], v[4:7]
	s_nop 7
	s_nop 1
	v_lshlrev_b32_e32 v8, 4, v1
	s_lshl_b32 s98, s3, 10
	v_add_u32_e32 v8, s98, v8
	s_cmp_lt_u32 s2, 4
	s_cbranch_scc1 .Llrn_lo1
	ds_write_b128 v8, v[4:7]
